# bf16 copy of the per-layer input p is produced by the P2 conv units (4 rows per wave) instead of the prologue phase; loop-top wait after conv covers the 8 trailing stores
# speedup vs baseline: 1.0126x; 1.0047x over previous
; #define GAS __attribute__((address_space(1)))
; __device__ __forceinline__ unsigned pk2(float lo, float hi) { return pg8::cvt_pk_bf16(lo, hi); }
; __device__ __forceinline__ void p0_prologue(const Args& a, LAS unsigned char* lds, int vcu, int G, int wave, int lane) {
;     ...
;     for (int i = 0; i < nrows; ++i) {
;         const int m = (!bal || i < 7) ? gw + NGW * i : (item_wave ? 15424 + (gw / 22) * 15 + gw % 22 : 14336 + w2 + 640 * (i - 7));
;         const GAS f32x4* xr = (const GAS f32x4*)(x + (size_t)m * DM) + lane;
;         f32x4 v[4]; float s = 0.f;
; #pragma unroll
;         for (int j = 0; j < 4; ++j) { v[j] = __builtin_nontemporal_load(&xr[64 * j]); s += (v[j].x * v[j].x + v[j].y * v[j].y) + (v[j].z * v[j].z + v[j].w * v[j].w); }
;         GAS unsigned long long* o8 = (GAS unsigned long long*)(XN + (size_t)m * DM) + lane;
; #pragma unroll
;         for (int j = 0; j < 4; ++j) o8[64 * j] = (unsigned long long)pk2(v[j].x, v[j].y) | ((unsigned long long)pk2(v[j].z, v[j].w) << 32);
;         const f32x4 pv = __builtin_nontemporal_load(&((const GAS f32x4*)(p + (size_t)m * PD))[lane]);
;         ((GAS unsigned long long*)(PB + (size_t)m * PD))[lane] = (unsigned long long)pk2(pv.x, pv.y) | ((unsigned long long)pk2(pv.z, pv.w) << 32);
;         s = wave_sum(s);
;         if (lane == 0) SS0[m] = s;
;     }
.LBB0_47:
	s_ashr_i32 s9, s8, 31
	s_lshl_b64 s[10:11], s[8:9], 12
	v_lshl_add_u64 v[24:25], v[4:5], 0, s[10:11]
	global_load_dwordx4 v[12:15], v[24:25], off nt
	global_load_dwordx4 v[16:19], v[24:25], off offset:1024 nt
	global_load_dwordx4 v[20:23], v[24:25], off offset:2048 nt
	s_nop 0
	global_load_dwordx4 v[24:27], v[24:25], off offset:3072 nt
	s_lshl_b64 s[26:27], s[8:9], 11
	v_lshl_add_u64 v[28:29], v[6:7], 0, s[26:27]
	s_lshl_b64 s[10:11], s[8:9], 10
	v_lshl_add_u64 v[30:31], v[8:9], 0, s[10:11]
	s_lshl_b64 s[10:11], s[8:9], 9
	s_waitcnt vmcnt(3)
	v_cvt_pk_bf16_f32 v32, v12, v13
	v_cvt_pk_bf16_f32 v33, v14, v15
	global_store_dwordx2 v[28:29], v[32:33], off
	s_waitcnt vmcnt(3)
	v_cvt_pk_bf16_f32 v32, v16, v17
	v_mul_f32_e32 v2, v13, v13
	v_mul_f32_e32 v13, v15, v15
	v_mul_f32_e32 v15, v17, v17
	v_mul_f32_e32 v17, v19, v19
	v_cvt_pk_bf16_f32 v33, v18, v19
	global_store_dwordx2 v[28:29], v[32:33], off offset:512
	s_waitcnt vmcnt(3)
	v_cvt_pk_bf16_f32 v32, v20, v21
	v_mul_f32_e32 v19, v21, v21
	v_mul_f32_e32 v21, v23, v23
	v_fmac_f32_e32 v13, v14, v14
	v_fmac_f32_e32 v15, v16, v16
	v_fmac_f32_e32 v17, v18, v18
	v_fmac_f32_e32 v2, v12, v12
	v_cvt_pk_bf16_f32 v33, v22, v23
	global_store_dwordx2 v[28:29], v[32:33], off offset:1024
	s_waitcnt vmcnt(3)
	v_cvt_pk_bf16_f32 v32, v24, v25
	v_mul_f32_e32 v23, v25, v25
	v_mul_f32_e32 v25, v27, v27
	v_fmac_f32_e32 v19, v20, v20
	v_fmac_f32_e32 v21, v22, v22
	v_add_f32_e32 v12, v15, v17
	v_add_f32_e32 v2, v2, v13
	v_fmac_f32_e32 v23, v24, v24
	v_fmac_f32_e32 v25, v26, v26
	v_add_f32_e32 v14, v19, v21
	v_add_f32_e32 v2, v2, v12
	v_add_f32_e32 v15, v23, v25
	v_add_f32_e32 v2, v2, v14
	v_add_f32_e32 v2, v2, v15
	v_cvt_pk_bf16_f32 v33, v26, v27
	global_store_dwordx2 v[28:29], v[32:33], off offset:1536
	v_add_f32_dpp v2, v2, v2 quad_perm:[1,0,3,2] row_mask:0xf bank_mask:0xf bound_ctrl:1
	s_nop 1
	v_add_f32_dpp v2, v2, v2 quad_perm:[2,3,0,1] row_mask:0xf bank_mask:0xf bound_ctrl:1
	s_nop 1
	v_add_f32_dpp v2, v2, v2 row_half_mirror row_mask:0xf bank_mask:0xf bound_ctrl:1
	s_nop 1
	v_add_f32_dpp v2, v2, v2 row_mirror row_mask:0xf bank_mask:0xf bound_ctrl:1
	v_mov_b32_e32 v12, v2
	s_nop 1
	v_permlane32_swap_b32_e32 v2, v12
	v_add_f32_e32 v2, v2, v12
	v_mov_b32_e32 v12, v2
	s_nop 1
	v_permlane16_swap_b32_e32 v2, v12
	s_and_saveexec_b64 s[10:11], s[0:1]
	s_cbranch_execz .LBB0_44
	s_lshl_b64 s[8:9], s[8:9], 2
	s_add_u32 s8, s13, s8
	v_add_f32_e32 v2, v2, v12
	s_addc_u32 s9, s15, s9
	global_store_dword v3, v2, s[8:9]
	s_branch .LBB0_44

; #define ATT_LDS_BAR() asm volatile("s_waitcnt lgkmcnt(0)\n\ts_barrier" ::: "memory")
; __global__ void __launch_bounds__(NWAVES * 64, 2) fwd(Args args) {
;     ...
;         for (;;) {
;             if (tid == 0) MISC[16] = nx;
;             ATT_LDS_BAR();
;             const int idx = __builtin_amdgcn_readfirstlane((int)MISC[16]);
;             ATT_LDS_BAR();
.LBB0_395:
	s_waitcnt vmcnt(8)
	v_mov_b32_e32 v188, v26
	s_mov_b64 s[26:27], s[2:3]
	s_branch .Lq_top_nowait

; #define LAS __attribute__((address_space(3)))
; __device__ __forceinline__ void conv_unit(int cu, const bf16* U, const unsigned char* cw16, const float* cb, const float* lg, const float* lb, bf16* MIX, LAS unsigned char* lds, int tid, int wave, int lane, bool& w_staged, unsigned& nx, gu32* qctr) {
;     asm volatile("" : "+v"(tid), "+v"(lane));
;     const int r0 = cu * CONV_ROWS;
;     const f32x4 b0 = *(const f32x4*)(cb + 8 * lane), b1 = *(const f32x4*)(cb + 8 * lane + 4);
;     const f32x4 g0 = *(const f32x4*)(lg + 8 * lane), g1 = *(const f32x4*)(lg + 8 * lane + 4), c0 = *(const f32x4*)(lb + 8 * lane), c1 = *(const f32x4*)(lb + 8 * lane + 4);
;     v4u wv[4] = {}; v4u uv[8];
; __global__ void __launch_bounds__(NWAVES * 64, 2) fwd(Args args) {
;     ...
;             } else {
;                 conv_unit(idx - n_att - w_p2, Ub, ws + WS_CW16, args.in[12], args.in[13], args.in[14], MIX, lds, tid, wave, lane, conv_w_staged, nx, ctl + CW_QUEUE);
.LBB0_462:
	s_mov_b64 s[2:3], -1
	s_cmp_ge_i32 s74, s95
	s_mov_b64 s[0:1], -1
	s_cbranch_scc0 .LBB0_492
	v_mov_b32_e32 v77, v0
	v_mov_b32_e32 v76, v206
	s_sub_i32 s58, s74, s95
	s_lshl_b32 s58, s58, 5
	s_lshl_b32 s59, s58, 10
	s_lshl_b32 s60, s58, 9
	v_readlane_b32 s24, v254, 4
	v_readlane_b32 s25, v254, 5
	v_and_b32_e32 v219, 0x1c0, v0
	v_and_b32_e32 v220, 63, v0
	v_lshlrev_b32_e32 v221, 5, v219
	v_lshlrev_b32_e32 v219, 6, v219
	v_lshl_or_b32 v219, v220, 4, v219
	v_lshl_or_b32 v221, v220, 3, v221
	s_add_u32 s24, s24, s59
	s_addc_u32 s25, s25, 0
	s_add_u32 s62, s22, 0xb800000
	s_addc_u32 s63, s23, 0
	s_add_u32 s62, s62, s60
	s_addc_u32 s63, s63, 0
	v_readlane_b32 s76, v254, 18
	v_readlane_b32 s77, v254, 19
	v_lshlrev_b32_e32 v74, 3, v76
	v_readlane_b32 s78, v254, 20
	v_readlane_b32 s79, v254, 21
	v_readlane_b32 s80, v254, 22
	v_readlane_b32 s81, v254, 23
	v_readlane_b32 s82, v254, 24
	v_readlane_b32 s83, v254, 25
	v_readlane_b32 s84, v254, 26
	v_readlane_b32 s85, v254, 27
	v_ashrrev_i32_e32 v75, 31, v74
	v_readlane_b32 s86, v254, 28
	v_readlane_b32 s87, v254, 29
	v_readlane_b32 s88, v254, 30
	v_readlane_b32 s89, v254, 31
	v_readlane_b32 s90, v254, 32
	v_readlane_b32 s91, v254, 33
	s_mov_b64 s[76:77], s[84:85]
	v_lshlrev_b64 v[6:7], 2, v[74:75]
	s_mov_b64 s[78:79], s[86:87]
	s_mov_b64 s[80:81], s[88:89]
	v_lshl_add_u64 v[2:3], s[76:77], 0, v[6:7]
	v_lshl_add_u64 v[8:9], s[78:79], 0, v[6:7]
	v_lshl_add_u64 v[10:11], s[80:81], 0, v[6:7]
	global_load_dwordx4 v[18:21], v[2:3], off offset:16
	global_load_dwordx4 v[22:25], v[2:3], off
	s_nop 0
	global_load_dwordx4 v[2:5], v[8:9], off offset:16
	global_load_dwordx4 v[14:17], v[8:9], off
	s_nop 0
	global_load_dwordx4 v[6:9], v[10:11], off offset:16
	s_nop 0
	global_load_dwordx4 v[10:13], v[10:11], off
	s_movk_i32 s0, 0x7c0
	s_mov_b64 s[14:15], -1
	s_and_b64 vcc, exec, s[4:5]
	v_cmp_gt_i32_e64 s[0:1], s0, v77
	v_add_u32_e32 v42, 0x200, v77
	v_add_u32_e32 v43, 0x400, v77
	v_add_u32_e32 v44, 0x600, v77
	s_mov_b64 s[82:83], s[90:91]
	s_cbranch_vccz .LBB0_465
	v_cndmask_b32_e64 v26, 0, v77, s[0:1]
	s_movk_i32 s0, 0x5c0
	v_readlane_b32 s8, v254, 44
	v_add_u32_e32 v80, 0x200, v77
	v_cmp_gt_i32_e32 vcc, s0, v77
	v_ashrrev_i32_e32 v27, 31, v26
	v_readlane_b32 s9, v254, 45
	v_cndmask_b32_e32 v28, 0, v80, vcc
	s_movk_i32 s0, 0x3c0
	v_lshl_add_u64 v[26:27], v[26:27], 4, s[8:9]
	v_ashrrev_i32_e32 v29, 31, v28
	v_add_u32_e32 v79, 0x400, v77
	v_cmp_gt_i32_e32 vcc, s0, v77
	s_movk_i32 s0, 0x1c0
	v_lshl_add_u64 v[28:29], v[28:29], 4, s[8:9]
	global_load_dwordx4 v[38:41], v[26:27], off
	global_load_dwordx4 v[30:33], v[28:29], off
	v_cndmask_b32_e32 v26, 0, v79, vcc
	v_add_u32_e32 v78, 0x600, v77
	v_cmp_gt_i32_e32 vcc, s0, v77
	v_ashrrev_i32_e32 v27, 31, v26
	v_lshl_add_u64 v[26:27], v[26:27], 4, s[8:9]
	v_cndmask_b32_e32 v28, 0, v78, vcc
	v_ashrrev_i32_e32 v29, 31, v28
	v_lshl_add_u64 v[28:29], v[28:29], 4, s[8:9]
	global_load_dwordx4 v[34:37], v[26:27], off
	s_nop 0
	global_load_dwordx4 v[26:29], v[28:29], off
	s_mov_b64 s[14:15], 0

; #define LAS __attribute__((address_space(3)))
; __device__ __forceinline__ void conv_unit(int cu, const bf16* U, const unsigned char* cw16, const float* cb, const float* lg, const float* lb, bf16* MIX, LAS unsigned char* lds, int tid, int wave, int lane, bool& w_staged, unsigned& nx, gu32* qctr) {
;     ...
;     __builtin_amdgcn_s_waitcnt(0x0F70);
;     if (tid == 0) nx = ticket_add(qctr);
;     asm volatile("s_waitcnt lgkmcnt(0)\n\ts_barrier" ::: "memory");
;     typedef _Float16 h2 __attribute__((ext_vector_type(2)));
;     h2 hacc[CONV_RW][4];
;     { const h2 i0 = __builtin_bit_cast(h2, __builtin_amdgcn_cvt_pkrtz(b0.x, b0.y)), i1 = __builtin_bit_cast(h2, __builtin_amdgcn_cvt_pkrtz(b0.z, b0.w)), i2 = __builtin_bit_cast(h2, __builtin_amdgcn_cvt_pkrtz(b1.x, b1.y)), i3 = __builtin_bit_cast(h2, __builtin_amdgcn_cvt_pkrtz(b1.z, b1.w));
; #pragma unroll
;       for (int j = 0; j < CONV_RW; ++j) { hacc[j][0] = i0; hacc[j][1] = i1; hacc[j][2] = i2; hacc[j][3] = i3; } }
;     {
;         typedef _Float16 h8 __attribute__((ext_vector_type(8)));
;         const LAS unsigned char* ub = lds + (wave * CONV_RW) * 1024 + lane * 16; const LAS unsigned char* wb = lds + CONV_W_LDS + lane * 16;
;         h8 uu[CONV_RW];
; #pragma unroll
;         for (int j = 0; j < CONV_RW - 1; ++j) uu[j] = *(const LAS h8*)(ub + j * 1024);
;         h8 kw = *(const LAS h8*)(wb);
; #pragma unroll
;         for (int t = 0; t < KC; ++t) {
;             uu[(t + CONV_RW - 1) & (CONV_RW - 1)] = *(const LAS h8*)(ub + (t + CONV_RW - 1) * 1024);
;             const h8 kwn = *(const LAS h8*)(wb + (t + 1 < KC ? t + 1 : t) * 1024);
;             const h2 k0 = __builtin_shufflevector(kw, kw, 0, 1), k1 = __builtin_shufflevector(kw, kw, 2, 3), k2 = __builtin_shufflevector(kw, kw, 4, 5), k3 = __builtin_shufflevector(kw, kw, 6, 7);
; #pragma unroll
;             for (int j = 0; j < CONV_RW; ++j) { const h8 u = uu[(t + j) & (CONV_RW - 1)];
;                 hacc[j][0] = __builtin_shufflevector(u, u, 0, 1) * k0 + hacc[j][0]; hacc[j][1] = __builtin_shufflevector(u, u, 2, 3) * k1 + hacc[j][1];
;                 hacc[j][2] = __builtin_shufflevector(u, u, 4, 5) * k2 + hacc[j][2]; hacc[j][3] = __builtin_shufflevector(u, u, 6, 7) * k3 + hacc[j][3]; }
;             kw = kwn;
.LBB0_489:
	s_or_b64 exec, exec, s[0:1]
	v_cmp_eq_u32_e32 vcc, 0, v77
	v_mov_b32_e32 v26, v188
	s_waitcnt vmcnt(0)
	global_load_dwordx4 v[130:133], v219, s[24:25] nt
	global_load_dwordx4 v[134:137], v219, s[24:25] offset:1024 nt
	global_load_dwordx4 v[138:141], v219, s[24:25] offset:2048 nt
	global_load_dwordx4 v[142:145], v219, s[24:25] offset:3072 nt
	s_and_saveexec_b64 s[0:1], vcc
	s_cbranch_execz .LBB0_491
	v_mov_b32_e32 v26, v199
	s_nop 0
	v_ashrrev_i32_e32 v27, 31, v26
	v_lshl_add_u64 v[26:27], v[26:27], 2, s[22:23]
	global_atomic_add v26, v[26:27], v215, off offset:256 sc0
.LBB0_491:
	s_or_b64 exec, exec, s[0:1]
	v_cvt_pkrtz_f16_f32 v24, v24, v25
	v_cvt_pkrtz_f16_f32 v25, v18, v19
	v_lshlrev_b32_e32 v19, 4, v76
	v_readlane_b32 s0, v254, 46
	s_waitcnt lgkmcnt(0)
	s_barrier
	v_cvt_pkrtz_f16_f32 v27, v22, v23
	v_cvt_pkrtz_f16_f32 v48, v20, v21
	v_add_u32_e32 v18, s0, v19
	v_add_u32_e32 v19, 0, v19
	v_add_u32_e32 v19, 0x10000, v19
	ds_read_b128 v[20:23], v19
	ds_read_b128 v[28:31], v18
	ds_read_b128 v[32:35], v18 offset:1024
	ds_read_b128 v[36:39], v18 offset:2048
	ds_read_b128 v[40:43], v18 offset:3072
	ds_read_b128 v[44:47], v19 offset:1024
	s_waitcnt lgkmcnt(4)
	v_pk_fma_f16 v49, v28, v20, v27
	v_pk_fma_f16 v50, v29, v21, v24
	v_pk_fma_f16 v51, v30, v22, v25
	v_pk_fma_f16 v52, v31, v23, v48
	s_waitcnt lgkmcnt(3)
	v_pk_fma_f16 v53, v32, v20, v27
	v_pk_fma_f16 v54, v33, v21, v24
	v_pk_fma_f16 v55, v34, v22, v25
	v_pk_fma_f16 v56, v35, v23, v48
	s_waitcnt lgkmcnt(2)
	v_pk_fma_f16 v57, v36, v20, v27
	v_pk_fma_f16 v58, v37, v21, v24
	v_pk_fma_f16 v59, v38, v22, v25
	v_pk_fma_f16 v60, v39, v23, v48
	s_waitcnt lgkmcnt(1)
	v_pk_fma_f16 v27, v20, v40, v27
	v_pk_fma_f16 v24, v21, v41, v24
	v_pk_fma_f16 v25, v22, v42, v25
	v_pk_fma_f16 v48, v23, v43, v48
	ds_read_b128 v[20:23], v18 offset:4096
	ds_read_b128 v[28:31], v19 offset:2048
	s_waitcnt lgkmcnt(2)
	v_pk_fma_f16 v49, v32, v44, v49
	v_pk_fma_f16 v50, v33, v45, v50
	v_pk_fma_f16 v51, v34, v46, v51
	v_pk_fma_f16 v52, v35, v47, v52
	ds_read_b128 v[32:35], v18 offset:5120
	v_pk_fma_f16 v53, v36, v44, v53
	v_pk_fma_f16 v54, v37, v45, v54
	v_pk_fma_f16 v55, v38, v46, v55
	v_pk_fma_f16 v56, v39, v47, v56
	v_pk_fma_f16 v57, v40, v44, v57
	v_pk_fma_f16 v58, v41, v45, v58
	v_pk_fma_f16 v59, v42, v46, v59
	v_pk_fma_f16 v60, v43, v47, v60
	s_waitcnt lgkmcnt(2)
	v_pk_fma_f16 v27, v44, v20, v27
	v_pk_fma_f16 v24, v45, v21, v24
	v_pk_fma_f16 v25, v46, v22, v25
	v_pk_fma_f16 v48, v47, v23, v48
	ds_read_b128 v[44:47], v19 offset:3072
	s_waitcnt lgkmcnt(2)
	v_pk_fma_f16 v49, v36, v28, v49
	v_pk_fma_f16 v50, v37, v29, v50
	v_pk_fma_f16 v51, v38, v30, v51
	v_pk_fma_f16 v52, v39, v31, v52
	v_pk_fma_f16 v53, v40, v28, v53
	v_pk_fma_f16 v54, v41, v29, v54
	v_pk_fma_f16 v55, v42, v30, v55
	v_pk_fma_f16 v56, v43, v31, v56
	v_pk_fma_f16 v57, v20, v28, v57
	v_pk_fma_f16 v58, v21, v29, v58
	v_pk_fma_f16 v59, v22, v30, v59
	v_pk_fma_f16 v60, v23, v31, v60
	s_waitcnt lgkmcnt(1)
	v_pk_fma_f16 v27, v28, v32, v27
	v_pk_fma_f16 v24, v29, v33, v24
	v_pk_fma_f16 v25, v30, v34, v25
	v_pk_fma_f16 v48, v31, v35, v48
	ds_read_b128 v[28:31], v18 offset:6144
	ds_read_b128 v[36:39], v19 offset:4096
	s_waitcnt lgkmcnt(2)
	v_pk_fma_f16 v49, v40, v44, v49
	v_pk_fma_f16 v50, v41, v45, v50
	v_pk_fma_f16 v51, v42, v46, v51
	v_pk_fma_f16 v52, v43, v47, v52
	ds_read_b128 v[40:43], v18 offset:7168
	v_pk_fma_f16 v53, v20, v44, v53
	v_pk_fma_f16 v54, v21, v45, v54
	v_pk_fma_f16 v55, v22, v46, v55
	v_pk_fma_f16 v56, v23, v47, v56
	v_pk_fma_f16 v57, v32, v44, v57
	v_pk_fma_f16 v58, v33, v45, v58
	v_pk_fma_f16 v59, v34, v46, v59
	v_pk_fma_f16 v60, v35, v47, v60
	s_waitcnt lgkmcnt(2)
	v_pk_fma_f16 v27, v44, v28, v27
	v_pk_fma_f16 v24, v45, v29, v24
	v_pk_fma_f16 v25, v46, v30, v25
	v_pk_fma_f16 v48, v47, v31, v48
	ds_read_b128 v[44:47], v19 offset:5120
	s_waitcnt lgkmcnt(2)
	v_pk_fma_f16 v49, v20, v36, v49
	v_pk_fma_f16 v50, v21, v37, v50
	v_pk_fma_f16 v51, v22, v38, v51
	v_pk_fma_f16 v52, v23, v39, v52
	v_pk_fma_f16 v53, v32, v36, v53
	v_pk_fma_f16 v54, v33, v37, v54
	v_pk_fma_f16 v55, v34, v38, v55
	v_pk_fma_f16 v56, v35, v39, v56
	v_pk_fma_f16 v57, v28, v36, v57
	v_pk_fma_f16 v58, v29, v37, v58
	v_pk_fma_f16 v59, v30, v38, v59
	v_pk_fma_f16 v60, v31, v39, v60
	s_waitcnt lgkmcnt(1)
	v_pk_fma_f16 v27, v36, v40, v27
	v_pk_fma_f16 v24, v37, v41, v24
	v_pk_fma_f16 v25, v38, v42, v25
	v_pk_fma_f16 v48, v39, v43, v48
	ds_read_b128 v[20:23], v18 offset:8192
	ds_read_b128 v[36:39], v19 offset:6144
	s_waitcnt lgkmcnt(2)
	v_pk_fma_f16 v49, v32, v44, v49
	v_pk_fma_f16 v50, v33, v45, v50
	v_pk_fma_f16 v51, v34, v46, v51
	v_pk_fma_f16 v52, v35, v47, v52
	ds_read_b128 v[32:35], v18 offset:9216
	v_pk_fma_f16 v53, v28, v44, v53
	v_pk_fma_f16 v54, v29, v45, v54
	v_pk_fma_f16 v55, v30, v46, v55
	v_pk_fma_f16 v56, v31, v47, v56
	v_pk_fma_f16 v57, v40, v44, v57
	v_pk_fma_f16 v58, v41, v45, v58
	v_pk_fma_f16 v59, v42, v46, v59
	v_pk_fma_f16 v60, v43, v47, v60
	s_waitcnt lgkmcnt(2)
	v_pk_fma_f16 v27, v44, v20, v27
	v_pk_fma_f16 v24, v45, v21, v24
	v_pk_fma_f16 v25, v46, v22, v25
	v_pk_fma_f16 v48, v47, v23, v48
	ds_read_b128 v[44:47], v19 offset:7168
	s_waitcnt lgkmcnt(2)
	v_pk_fma_f16 v49, v28, v36, v49
	v_pk_fma_f16 v50, v29, v37, v50
	v_pk_fma_f16 v51, v30, v38, v51
	v_pk_fma_f16 v52, v31, v39, v52
	v_pk_fma_f16 v53, v40, v36, v53
	v_pk_fma_f16 v54, v41, v37, v54
	v_pk_fma_f16 v55, v42, v38, v55
	v_pk_fma_f16 v56, v43, v39, v56
	v_pk_fma_f16 v57, v20, v36, v57
	v_pk_fma_f16 v58, v21, v37, v58
	v_pk_fma_f16 v59, v22, v38, v59
	v_pk_fma_f16 v60, v23, v39, v60
	s_waitcnt lgkmcnt(1)
; #define LAS __attribute__((address_space(3)))
; __device__ __forceinline__ void conv_unit(int cu, const bf16* U, const unsigned char* cw16, const float* cb, const float* lg, const float* lb, bf16* MIX, LAS unsigned char* lds, int tid, int wave, int lane, bool& w_staged, unsigned& nx, gu32* qctr) {
;     ...
;         for (int t = 0; t < KC; ++t) {
;             uu[(t + CONV_RW - 1) & (CONV_RW - 1)] = *(const LAS h8*)(ub + (t + CONV_RW - 1) * 1024);
;             const h8 kwn = *(const LAS h8*)(wb + (t + 1 < KC ? t + 1 : t) * 1024);
;             const h2 k0 = __builtin_shufflevector(kw, kw, 0, 1), k1 = __builtin_shufflevector(kw, kw, 2, 3), k2 = __builtin_shufflevector(kw, kw, 4, 5), k3 = __builtin_shufflevector(kw, kw, 6, 7);
; #pragma unroll
;             for (int j = 0; j < CONV_RW; ++j) { const h8 u = uu[(t + j) & (CONV_RW - 1)];
;                 hacc[j][0] = __builtin_shufflevector(u, u, 0, 1) * k0 + hacc[j][0]; hacc[j][1] = __builtin_shufflevector(u, u, 2, 3) * k1 + hacc[j][1];
;                 hacc[j][2] = __builtin_shufflevector(u, u, 4, 5) * k2 + hacc[j][2]; hacc[j][3] = __builtin_shufflevector(u, u, 6, 7) * k3 + hacc[j][3]; }
;             kw = kwn;
	v_pk_fma_f16 v27, v36, v32, v27
	v_pk_fma_f16 v24, v37, v33, v24
	v_pk_fma_f16 v25, v38, v34, v25
	v_pk_fma_f16 v48, v39, v35, v48
	ds_read_b128 v[28:31], v18 offset:10240
	ds_read_b128 v[36:39], v19 offset:8192
	s_waitcnt lgkmcnt(2)
	v_pk_fma_f16 v49, v40, v44, v49
	v_pk_fma_f16 v50, v41, v45, v50
	v_pk_fma_f16 v51, v42, v46, v51
	v_pk_fma_f16 v52, v43, v47, v52
	ds_read_b128 v[40:43], v18 offset:11264
	v_pk_fma_f16 v53, v20, v44, v53
	v_pk_fma_f16 v54, v21, v45, v54
	v_pk_fma_f16 v55, v22, v46, v55
	v_pk_fma_f16 v56, v23, v47, v56
	v_pk_fma_f16 v57, v32, v44, v57
	v_pk_fma_f16 v58, v33, v45, v58
	v_pk_fma_f16 v59, v34, v46, v59
	v_pk_fma_f16 v60, v35, v47, v60
	s_waitcnt lgkmcnt(2)
	v_pk_fma_f16 v27, v44, v28, v27
	v_pk_fma_f16 v24, v45, v29, v24
	v_pk_fma_f16 v25, v46, v30, v25
	v_pk_fma_f16 v48, v47, v31, v48
	ds_read_b128 v[44:47], v19 offset:9216
	s_waitcnt lgkmcnt(2)
	v_pk_fma_f16 v49, v20, v36, v49
	v_pk_fma_f16 v50, v21, v37, v50
	v_pk_fma_f16 v51, v22, v38, v51
	v_pk_fma_f16 v52, v23, v39, v52
	v_pk_fma_f16 v53, v32, v36, v53
	v_pk_fma_f16 v54, v33, v37, v54
	v_pk_fma_f16 v55, v34, v38, v55
	v_pk_fma_f16 v56, v35, v39, v56
	v_pk_fma_f16 v57, v28, v36, v57
	v_pk_fma_f16 v58, v29, v37, v58
	v_pk_fma_f16 v59, v30, v38, v59
	v_pk_fma_f16 v60, v31, v39, v60
	s_waitcnt lgkmcnt(1)
	v_pk_fma_f16 v27, v36, v40, v27
	v_pk_fma_f16 v24, v37, v41, v24
	v_pk_fma_f16 v25, v38, v42, v25
	v_pk_fma_f16 v48, v39, v43, v48
	ds_read_b128 v[20:23], v18 offset:12288
	ds_read_b128 v[36:39], v19 offset:10240
	s_waitcnt lgkmcnt(2)
	v_pk_fma_f16 v49, v32, v44, v49
	v_pk_fma_f16 v50, v33, v45, v50
	v_pk_fma_f16 v51, v34, v46, v51
	v_pk_fma_f16 v52, v35, v47, v52
	ds_read_b128 v[32:35], v18 offset:13312
	v_pk_fma_f16 v53, v28, v44, v53
	v_pk_fma_f16 v54, v29, v45, v54
	v_pk_fma_f16 v55, v30, v46, v55
	v_pk_fma_f16 v56, v31, v47, v56
	v_pk_fma_f16 v57, v40, v44, v57
	v_pk_fma_f16 v58, v41, v45, v58
	v_pk_fma_f16 v59, v42, v46, v59
	v_pk_fma_f16 v60, v43, v47, v60
	s_waitcnt lgkmcnt(2)
	v_pk_fma_f16 v27, v44, v20, v27
	v_pk_fma_f16 v24, v45, v21, v24
	v_pk_fma_f16 v25, v46, v22, v25
	v_pk_fma_f16 v48, v47, v23, v48
	ds_read_b128 v[44:47], v19 offset:11264
	s_waitcnt lgkmcnt(2)
	v_pk_fma_f16 v49, v28, v36, v49
	v_pk_fma_f16 v50, v29, v37, v50
	v_pk_fma_f16 v51, v30, v38, v51
	v_pk_fma_f16 v52, v31, v39, v52
	v_pk_fma_f16 v53, v40, v36, v53
	v_pk_fma_f16 v54, v41, v37, v54
	v_pk_fma_f16 v55, v42, v38, v55
	v_pk_fma_f16 v56, v43, v39, v56
	v_pk_fma_f16 v57, v20, v36, v57
	v_pk_fma_f16 v58, v21, v37, v58
	v_pk_fma_f16 v59, v22, v38, v59
	v_pk_fma_f16 v60, v23, v39, v60
	s_waitcnt lgkmcnt(1)
	v_pk_fma_f16 v27, v36, v32, v27
	v_pk_fma_f16 v24, v37, v33, v24
	v_pk_fma_f16 v25, v38, v34, v25
	v_pk_fma_f16 v48, v39, v35, v48
	ds_read_b128 v[28:31], v18 offset:14336
	ds_read_b128 v[36:39], v19 offset:12288
	s_waitcnt lgkmcnt(2)
	v_pk_fma_f16 v49, v40, v44, v49
	v_pk_fma_f16 v50, v41, v45, v50
	v_pk_fma_f16 v51, v42, v46, v51
	v_pk_fma_f16 v52, v43, v47, v52
	ds_read_b128 v[40:43], v18 offset:15360
	v_pk_fma_f16 v53, v20, v44, v53
	v_pk_fma_f16 v54, v21, v45, v54
	v_pk_fma_f16 v55, v22, v46, v55
	v_pk_fma_f16 v56, v23, v47, v56
	v_pk_fma_f16 v57, v32, v44, v57
	v_pk_fma_f16 v58, v33, v45, v58
	v_pk_fma_f16 v59, v34, v46, v59
	v_pk_fma_f16 v60, v35, v47, v60
	s_waitcnt lgkmcnt(2)
	v_pk_fma_f16 v27, v44, v28, v27
	v_pk_fma_f16 v24, v45, v29, v24
	v_pk_fma_f16 v25, v46, v30, v25
	v_pk_fma_f16 v48, v47, v31, v48
	ds_read_b128 v[44:47], v19 offset:13312
	s_waitcnt lgkmcnt(2)
	v_pk_fma_f16 v49, v20, v36, v49
	v_pk_fma_f16 v50, v21, v37, v50
	v_pk_fma_f16 v51, v22, v38, v51
	v_pk_fma_f16 v52, v23, v39, v52
	v_pk_fma_f16 v53, v32, v36, v53
	v_pk_fma_f16 v54, v33, v37, v54
	v_pk_fma_f16 v55, v34, v38, v55
	v_pk_fma_f16 v56, v35, v39, v56
	v_pk_fma_f16 v57, v28, v36, v57
	v_pk_fma_f16 v58, v29, v37, v58
	v_pk_fma_f16 v59, v30, v38, v59
	v_pk_fma_f16 v60, v31, v39, v60
	s_waitcnt lgkmcnt(1)
	v_pk_fma_f16 v27, v36, v40, v27
	v_pk_fma_f16 v24, v37, v41, v24
	v_pk_fma_f16 v25, v38, v42, v25
	v_pk_fma_f16 v48, v39, v43, v48
	ds_read_b128 v[20:23], v18 offset:16384
	ds_read_b128 v[36:39], v19 offset:14336
	s_waitcnt lgkmcnt(2)
	v_pk_fma_f16 v49, v32, v44, v49
	v_pk_fma_f16 v50, v33, v45, v50
	v_pk_fma_f16 v51, v34, v46, v51
	v_pk_fma_f16 v52, v35, v47, v52
	ds_read_b128 v[32:35], v18 offset:17408
	v_pk_fma_f16 v53, v28, v44, v53
	v_pk_fma_f16 v54, v29, v45, v54
	v_pk_fma_f16 v55, v30, v46, v55
	v_pk_fma_f16 v56, v31, v47, v56
	v_pk_fma_f16 v57, v40, v44, v57
	v_pk_fma_f16 v58, v41, v45, v58
	v_pk_fma_f16 v59, v42, v46, v59
	v_pk_fma_f16 v60, v43, v47, v60
	s_waitcnt lgkmcnt(2)
	v_pk_fma_f16 v27, v44, v20, v27
	v_pk_fma_f16 v24, v45, v21, v24
	v_pk_fma_f16 v25, v46, v22, v25
	v_pk_fma_f16 v48, v47, v23, v48
	ds_read_b128 v[44:47], v19 offset:15360
	s_waitcnt lgkmcnt(2)
	v_pk_fma_f16 v49, v28, v36, v49
	v_pk_fma_f16 v50, v29, v37, v50
	v_pk_fma_f16 v51, v30, v38, v51
	v_pk_fma_f16 v52, v31, v39, v52
	v_pk_fma_f16 v53, v40, v36, v53
	v_pk_fma_f16 v54, v41, v37, v54
	v_pk_fma_f16 v55, v42, v38, v55
	v_pk_fma_f16 v56, v43, v39, v56
	v_pk_fma_f16 v57, v20, v36, v57
	v_pk_fma_f16 v58, v21, v37, v58
	v_pk_fma_f16 v59, v22, v38, v59
	v_pk_fma_f16 v60, v23, v39, v60
	s_waitcnt lgkmcnt(1)
	v_pk_fma_f16 v27, v36, v32, v27
	v_pk_fma_f16 v24, v37, v33, v24
	v_pk_fma_f16 v25, v38, v34, v25
	v_pk_fma_f16 v48, v39, v35, v48
	ds_read_b128 v[28:31], v18 offset:18432
	ds_read_b128 v[36:39], v19 offset:16384
	s_waitcnt lgkmcnt(2)
; #define LAS __attribute__((address_space(3)))
; __device__ __forceinline__ void conv_unit(int cu, const bf16* U, const unsigned char* cw16, const float* cb, const float* lg, const float* lb, bf16* MIX, LAS unsigned char* lds, int tid, int wave, int lane, bool& w_staged, unsigned& nx, gu32* qctr) {
;     ...
;         for (int t = 0; t < KC; ++t) {
;             uu[(t + CONV_RW - 1) & (CONV_RW - 1)] = *(const LAS h8*)(ub + (t + CONV_RW - 1) * 1024);
;             const h8 kwn = *(const LAS h8*)(wb + (t + 1 < KC ? t + 1 : t) * 1024);
;             const h2 k0 = __builtin_shufflevector(kw, kw, 0, 1), k1 = __builtin_shufflevector(kw, kw, 2, 3), k2 = __builtin_shufflevector(kw, kw, 4, 5), k3 = __builtin_shufflevector(kw, kw, 6, 7);
; #pragma unroll
;             for (int j = 0; j < CONV_RW; ++j) { const h8 u = uu[(t + j) & (CONV_RW - 1)];
;                 hacc[j][0] = __builtin_shufflevector(u, u, 0, 1) * k0 + hacc[j][0]; hacc[j][1] = __builtin_shufflevector(u, u, 2, 3) * k1 + hacc[j][1];
;                 hacc[j][2] = __builtin_shufflevector(u, u, 4, 5) * k2 + hacc[j][2]; hacc[j][3] = __builtin_shufflevector(u, u, 6, 7) * k3 + hacc[j][3]; }
;             kw = kwn;
	v_pk_fma_f16 v49, v40, v44, v49
	v_pk_fma_f16 v50, v41, v45, v50
	v_pk_fma_f16 v51, v42, v46, v51
	v_pk_fma_f16 v52, v43, v47, v52
	ds_read_b128 v[40:43], v18 offset:19456
	v_pk_fma_f16 v53, v20, v44, v53
	v_pk_fma_f16 v54, v21, v45, v54
	v_pk_fma_f16 v55, v22, v46, v55
	v_pk_fma_f16 v56, v23, v47, v56
	v_pk_fma_f16 v57, v32, v44, v57
	v_pk_fma_f16 v58, v33, v45, v58
	v_pk_fma_f16 v59, v34, v46, v59
	v_pk_fma_f16 v60, v35, v47, v60
	s_waitcnt lgkmcnt(2)
	v_pk_fma_f16 v27, v44, v28, v27
	v_pk_fma_f16 v24, v45, v29, v24
	v_pk_fma_f16 v25, v46, v30, v25
	v_pk_fma_f16 v48, v47, v31, v48
	ds_read_b128 v[44:47], v19 offset:17408
	s_waitcnt lgkmcnt(2)
	v_pk_fma_f16 v49, v20, v36, v49
	v_pk_fma_f16 v50, v21, v37, v50
	v_pk_fma_f16 v51, v22, v38, v51
	v_pk_fma_f16 v52, v23, v39, v52
	v_pk_fma_f16 v53, v32, v36, v53
	v_pk_fma_f16 v54, v33, v37, v54
	v_pk_fma_f16 v55, v34, v38, v55
	v_pk_fma_f16 v56, v35, v39, v56
	v_pk_fma_f16 v57, v28, v36, v57
	v_pk_fma_f16 v58, v29, v37, v58
	v_pk_fma_f16 v59, v30, v38, v59
	v_pk_fma_f16 v60, v31, v39, v60
	s_waitcnt lgkmcnt(1)
	v_pk_fma_f16 v27, v36, v40, v27
	v_pk_fma_f16 v24, v37, v41, v24
	v_pk_fma_f16 v25, v38, v42, v25
	v_pk_fma_f16 v48, v39, v43, v48
	ds_read_b128 v[20:23], v18 offset:20480
	ds_read_b128 v[36:39], v19 offset:18432
	s_waitcnt lgkmcnt(2)
	v_pk_fma_f16 v49, v32, v44, v49
	v_pk_fma_f16 v50, v33, v45, v50
	v_pk_fma_f16 v51, v34, v46, v51
	v_pk_fma_f16 v52, v35, v47, v52
	ds_read_b128 v[32:35], v18 offset:21504
	v_pk_fma_f16 v53, v28, v44, v53
	v_pk_fma_f16 v54, v29, v45, v54
	v_pk_fma_f16 v55, v30, v46, v55
	v_pk_fma_f16 v56, v31, v47, v56
	v_pk_fma_f16 v57, v40, v44, v57
	v_pk_fma_f16 v58, v41, v45, v58
	v_pk_fma_f16 v59, v42, v46, v59
	v_pk_fma_f16 v60, v43, v47, v60
	s_waitcnt lgkmcnt(2)
	v_pk_fma_f16 v27, v44, v20, v27
	v_pk_fma_f16 v24, v45, v21, v24
	v_pk_fma_f16 v25, v46, v22, v25
	v_pk_fma_f16 v48, v47, v23, v48
	ds_read_b128 v[44:47], v19 offset:19456
	s_waitcnt lgkmcnt(2)
	v_pk_fma_f16 v49, v28, v36, v49
	v_pk_fma_f16 v50, v29, v37, v50
	v_pk_fma_f16 v51, v30, v38, v51
	v_pk_fma_f16 v52, v31, v39, v52
	v_pk_fma_f16 v53, v40, v36, v53
	v_pk_fma_f16 v54, v41, v37, v54
	v_pk_fma_f16 v55, v42, v38, v55
	v_pk_fma_f16 v56, v43, v39, v56
	v_pk_fma_f16 v57, v20, v36, v57
	v_pk_fma_f16 v58, v21, v37, v58
	v_pk_fma_f16 v59, v22, v38, v59
	v_pk_fma_f16 v60, v23, v39, v60
	s_waitcnt lgkmcnt(1)
	v_pk_fma_f16 v27, v36, v32, v27
	v_pk_fma_f16 v24, v37, v33, v24
	v_pk_fma_f16 v25, v38, v34, v25
	v_pk_fma_f16 v48, v39, v35, v48
	ds_read_b128 v[28:31], v18 offset:22528
	ds_read_b128 v[36:39], v19 offset:20480
	s_waitcnt lgkmcnt(2)
	v_pk_fma_f16 v49, v40, v44, v49
	v_pk_fma_f16 v50, v41, v45, v50
	v_pk_fma_f16 v51, v42, v46, v51
	v_pk_fma_f16 v52, v43, v47, v52
	ds_read_b128 v[40:43], v18 offset:23552
	v_pk_fma_f16 v53, v20, v44, v53
	v_pk_fma_f16 v54, v21, v45, v54
	v_pk_fma_f16 v55, v22, v46, v55
	v_pk_fma_f16 v56, v23, v47, v56
	v_pk_fma_f16 v57, v32, v44, v57
	v_pk_fma_f16 v58, v33, v45, v58
	v_pk_fma_f16 v59, v34, v46, v59
	v_pk_fma_f16 v60, v35, v47, v60
	s_waitcnt lgkmcnt(2)
	v_pk_fma_f16 v27, v44, v28, v27
	v_pk_fma_f16 v24, v45, v29, v24
	v_pk_fma_f16 v25, v46, v30, v25
	v_pk_fma_f16 v48, v47, v31, v48
	ds_read_b128 v[44:47], v19 offset:21504
	s_waitcnt lgkmcnt(2)
	v_pk_fma_f16 v49, v20, v36, v49
	v_pk_fma_f16 v50, v21, v37, v50
	v_pk_fma_f16 v51, v22, v38, v51
	v_pk_fma_f16 v52, v23, v39, v52
	v_pk_fma_f16 v53, v32, v36, v53
	v_pk_fma_f16 v54, v33, v37, v54
	v_pk_fma_f16 v55, v34, v38, v55
	v_pk_fma_f16 v56, v35, v39, v56
	v_pk_fma_f16 v57, v28, v36, v57
	v_pk_fma_f16 v58, v29, v37, v58
	v_pk_fma_f16 v59, v30, v38, v59
	v_pk_fma_f16 v60, v31, v39, v60
	s_waitcnt lgkmcnt(1)
	v_pk_fma_f16 v27, v36, v40, v27
	v_pk_fma_f16 v24, v37, v41, v24
	v_pk_fma_f16 v25, v38, v42, v25
	v_pk_fma_f16 v48, v39, v43, v48
	ds_read_b128 v[20:23], v18 offset:24576
	ds_read_b128 v[36:39], v19 offset:22528
	s_waitcnt lgkmcnt(2)
	v_pk_fma_f16 v49, v32, v44, v49
	v_pk_fma_f16 v50, v33, v45, v50
	v_pk_fma_f16 v51, v34, v46, v51
	v_pk_fma_f16 v52, v35, v47, v52
	ds_read_b128 v[32:35], v18 offset:25600
	v_pk_fma_f16 v53, v28, v44, v53
	v_pk_fma_f16 v54, v29, v45, v54
	v_pk_fma_f16 v55, v30, v46, v55
	v_pk_fma_f16 v56, v31, v47, v56
	v_pk_fma_f16 v57, v40, v44, v57
	v_pk_fma_f16 v58, v41, v45, v58
	v_pk_fma_f16 v59, v42, v46, v59
	v_pk_fma_f16 v60, v43, v47, v60
	s_waitcnt lgkmcnt(2)
	v_pk_fma_f16 v27, v44, v20, v27
	v_pk_fma_f16 v24, v45, v21, v24
	v_pk_fma_f16 v25, v46, v22, v25
	v_pk_fma_f16 v48, v47, v23, v48
	ds_read_b128 v[44:47], v19 offset:23552
	s_waitcnt lgkmcnt(2)
	v_pk_fma_f16 v49, v28, v36, v49
	v_pk_fma_f16 v50, v29, v37, v50
	v_pk_fma_f16 v51, v30, v38, v51
	v_pk_fma_f16 v52, v31, v39, v52
	v_pk_fma_f16 v53, v40, v36, v53
	v_pk_fma_f16 v54, v41, v37, v54
	v_pk_fma_f16 v55, v42, v38, v55
	v_pk_fma_f16 v56, v43, v39, v56
	v_pk_fma_f16 v57, v20, v36, v57
	v_pk_fma_f16 v58, v21, v37, v58
	v_pk_fma_f16 v59, v22, v38, v59
	v_pk_fma_f16 v60, v23, v39, v60
	s_waitcnt lgkmcnt(1)
	v_pk_fma_f16 v27, v36, v32, v27
	v_pk_fma_f16 v24, v37, v33, v24
	v_pk_fma_f16 v25, v38, v34, v25
	v_pk_fma_f16 v48, v39, v35, v48
	ds_read_b128 v[28:31], v18 offset:26624
	ds_read_b128 v[36:39], v19 offset:24576
	s_waitcnt lgkmcnt(2)
	v_pk_fma_f16 v49, v40, v44, v49
	v_pk_fma_f16 v50, v41, v45, v50
	v_pk_fma_f16 v51, v42, v46, v51
	v_pk_fma_f16 v52, v43, v47, v52
	ds_read_b128 v[40:43], v18 offset:27648
	v_pk_fma_f16 v53, v20, v44, v53
	v_pk_fma_f16 v54, v21, v45, v54
	v_pk_fma_f16 v55, v22, v46, v55
	v_pk_fma_f16 v56, v23, v47, v56
	v_pk_fma_f16 v57, v32, v44, v57
	v_pk_fma_f16 v58, v33, v45, v58
	v_pk_fma_f16 v59, v34, v46, v59
	v_pk_fma_f16 v60, v35, v47, v60
	s_waitcnt lgkmcnt(2)
; #define LAS __attribute__((address_space(3)))
; __device__ __forceinline__ void conv_unit(int cu, const bf16* U, const unsigned char* cw16, const float* cb, const float* lg, const float* lb, bf16* MIX, LAS unsigned char* lds, int tid, int wave, int lane, bool& w_staged, unsigned& nx, gu32* qctr) {
;     ...
;         for (int t = 0; t < KC; ++t) {
;             uu[(t + CONV_RW - 1) & (CONV_RW - 1)] = *(const LAS h8*)(ub + (t + CONV_RW - 1) * 1024);
;             const h8 kwn = *(const LAS h8*)(wb + (t + 1 < KC ? t + 1 : t) * 1024);
;             const h2 k0 = __builtin_shufflevector(kw, kw, 0, 1), k1 = __builtin_shufflevector(kw, kw, 2, 3), k2 = __builtin_shufflevector(kw, kw, 4, 5), k3 = __builtin_shufflevector(kw, kw, 6, 7);
; #pragma unroll
;             for (int j = 0; j < CONV_RW; ++j) { const h8 u = uu[(t + j) & (CONV_RW - 1)];
;                 hacc[j][0] = __builtin_shufflevector(u, u, 0, 1) * k0 + hacc[j][0]; hacc[j][1] = __builtin_shufflevector(u, u, 2, 3) * k1 + hacc[j][1];
;                 hacc[j][2] = __builtin_shufflevector(u, u, 4, 5) * k2 + hacc[j][2]; hacc[j][3] = __builtin_shufflevector(u, u, 6, 7) * k3 + hacc[j][3]; }
;             kw = kwn;
	v_pk_fma_f16 v27, v44, v28, v27
	v_pk_fma_f16 v24, v45, v29, v24
	v_pk_fma_f16 v25, v46, v30, v25
	v_pk_fma_f16 v48, v47, v31, v48
	ds_read_b128 v[44:47], v19 offset:25600
	s_waitcnt lgkmcnt(2)
	v_pk_fma_f16 v49, v20, v36, v49
	v_pk_fma_f16 v50, v21, v37, v50
	v_pk_fma_f16 v51, v22, v38, v51
	v_pk_fma_f16 v52, v23, v39, v52
	v_pk_fma_f16 v53, v32, v36, v53
	v_pk_fma_f16 v54, v33, v37, v54
	v_pk_fma_f16 v55, v34, v38, v55
	v_pk_fma_f16 v56, v35, v39, v56
	v_pk_fma_f16 v57, v28, v36, v57
	v_pk_fma_f16 v58, v29, v37, v58
	v_pk_fma_f16 v59, v30, v38, v59
	v_pk_fma_f16 v60, v31, v39, v60
	s_waitcnt lgkmcnt(1)
	v_pk_fma_f16 v27, v36, v40, v27
	v_pk_fma_f16 v24, v37, v41, v24
	v_pk_fma_f16 v25, v38, v42, v25
	v_pk_fma_f16 v48, v39, v43, v48
	ds_read_b128 v[20:23], v18 offset:28672
	ds_read_b128 v[36:39], v19 offset:26624
	s_waitcnt lgkmcnt(2)
	v_pk_fma_f16 v49, v32, v44, v49
	v_pk_fma_f16 v50, v33, v45, v50
	v_pk_fma_f16 v51, v34, v46, v51
	v_pk_fma_f16 v52, v35, v47, v52
	ds_read_b128 v[32:35], v18 offset:29696
	v_pk_fma_f16 v53, v28, v44, v53
	v_pk_fma_f16 v54, v29, v45, v54
	v_pk_fma_f16 v55, v30, v46, v55
	v_pk_fma_f16 v56, v31, v47, v56
	v_pk_fma_f16 v57, v40, v44, v57
	v_pk_fma_f16 v58, v41, v45, v58
	v_pk_fma_f16 v59, v42, v46, v59
	v_pk_fma_f16 v60, v43, v47, v60
	s_waitcnt lgkmcnt(2)
	v_pk_fma_f16 v27, v44, v20, v27
	v_pk_fma_f16 v24, v45, v21, v24
	v_pk_fma_f16 v25, v46, v22, v25
	v_pk_fma_f16 v48, v47, v23, v48
	ds_read_b128 v[44:47], v19 offset:27648
	s_waitcnt lgkmcnt(2)
	v_pk_fma_f16 v49, v28, v36, v49
	v_pk_fma_f16 v50, v29, v37, v50
	v_pk_fma_f16 v51, v30, v38, v51
	v_pk_fma_f16 v52, v31, v39, v52
	v_pk_fma_f16 v53, v40, v36, v53
	v_pk_fma_f16 v54, v41, v37, v54
	v_pk_fma_f16 v55, v42, v38, v55
	v_pk_fma_f16 v56, v43, v39, v56
	v_pk_fma_f16 v57, v20, v36, v57
	v_pk_fma_f16 v58, v21, v37, v58
	v_pk_fma_f16 v59, v22, v38, v59
	v_pk_fma_f16 v60, v23, v39, v60
	s_waitcnt lgkmcnt(1)
	v_pk_fma_f16 v27, v36, v32, v27
	v_pk_fma_f16 v24, v37, v33, v24
	v_pk_fma_f16 v25, v38, v34, v25
	v_pk_fma_f16 v48, v39, v35, v48
	ds_read_b128 v[28:31], v18 offset:30720
	ds_read_b128 v[36:39], v19 offset:28672
	s_waitcnt lgkmcnt(2)
	v_pk_fma_f16 v49, v40, v44, v49
	v_pk_fma_f16 v50, v41, v45, v50
	v_pk_fma_f16 v51, v42, v46, v51
	v_pk_fma_f16 v52, v43, v47, v52
	ds_read_b128 v[40:43], v18 offset:31744
	v_pk_fma_f16 v53, v20, v44, v53
	v_pk_fma_f16 v54, v21, v45, v54
	v_pk_fma_f16 v55, v22, v46, v55
	v_pk_fma_f16 v56, v23, v47, v56
	v_pk_fma_f16 v57, v32, v44, v57
	v_pk_fma_f16 v58, v33, v45, v58
	v_pk_fma_f16 v59, v34, v46, v59
	v_pk_fma_f16 v60, v35, v47, v60
	s_waitcnt lgkmcnt(2)
	v_pk_fma_f16 v27, v44, v28, v27
	v_pk_fma_f16 v24, v45, v29, v24
	v_pk_fma_f16 v25, v46, v30, v25
	v_pk_fma_f16 v48, v47, v31, v48
	ds_read_b128 v[44:47], v19 offset:29696
	s_waitcnt lgkmcnt(2)
	v_pk_fma_f16 v49, v20, v36, v49
	v_pk_fma_f16 v50, v21, v37, v50
	v_pk_fma_f16 v51, v22, v38, v51
	v_pk_fma_f16 v52, v23, v39, v52
	v_pk_fma_f16 v53, v32, v36, v53
	v_pk_fma_f16 v54, v33, v37, v54
	v_pk_fma_f16 v55, v34, v38, v55
	v_pk_fma_f16 v56, v35, v39, v56
	v_pk_fma_f16 v57, v28, v36, v57
	v_pk_fma_f16 v58, v29, v37, v58
	v_pk_fma_f16 v59, v30, v38, v59
	v_pk_fma_f16 v60, v31, v39, v60
	s_waitcnt lgkmcnt(1)
	v_pk_fma_f16 v27, v36, v40, v27
	v_pk_fma_f16 v24, v37, v41, v24
	v_pk_fma_f16 v25, v38, v42, v25
	v_pk_fma_f16 v48, v39, v43, v48
	ds_read_b128 v[20:23], v18 offset:32768
	ds_read_b128 v[36:39], v19 offset:30720
	s_waitcnt lgkmcnt(2)
	v_pk_fma_f16 v19, v32, v44, v49
	v_pk_fma_f16 v49, v33, v45, v50
	v_pk_fma_f16 v50, v34, v46, v51
	v_pk_fma_f16 v51, v35, v47, v52
	ds_read_b128 v[32:35], v18 offset:33792
	v_pk_fma_f16 v52, v28, v44, v53
	v_pk_fma_f16 v53, v29, v45, v54
	v_pk_fma_f16 v54, v30, v46, v55
	v_pk_fma_f16 v55, v31, v47, v56
	v_pk_fma_f16 v56, v40, v44, v57
	v_pk_fma_f16 v57, v41, v45, v58
	v_pk_fma_f16 v58, v42, v46, v59
	v_pk_fma_f16 v59, v43, v47, v60
	s_waitcnt lgkmcnt(2)
	v_pk_fma_f16 v18, v44, v20, v27
	v_pk_fma_f16 v24, v45, v21, v24
	v_pk_fma_f16 v27, v46, v22, v25
	v_pk_fma_f16 v44, v47, v23, v48
	s_waitcnt lgkmcnt(1)
	v_pk_fma_f16 v45, v28, v36, v19
	v_pk_fma_f16 v46, v29, v37, v49
	v_pk_fma_f16 v47, v30, v38, v50
	v_pk_fma_f16 v48, v31, v39, v51
	v_pk_fma_f16 v49, v20, v36, v56
	v_pk_fma_f16 v50, v21, v37, v57
	s_waitcnt lgkmcnt(0)
; #define GAS __attribute__((address_space(1)))
; __device__ __forceinline__ unsigned pk2(float lo, float hi) { return pg8::cvt_pk_bf16(lo, hi); }
; __device__ __forceinline__ void conv_unit(int cu, const bf16* U, const unsigned char* cw16, const float* cb, const float* lg, const float* lb, bf16* MIX, LAS unsigned char* lds, int tid, int wave, int lane, bool& w_staged, unsigned& nx, gu32* qctr) {
;     ...
; #pragma unroll
;     for (int j = 0; j < CONV_RW; ++j) {
;         f32x4 a0 = {(float)hacc[j][0][0], (float)hacc[j][0][1], (float)hacc[j][1][0], (float)hacc[j][1][1]}, a1 = {(float)hacc[j][2][0], (float)hacc[j][2][1], (float)hacc[j][3][0], (float)hacc[j][3][1]};
;         const f32x4 s4 = a0 + a1;
;         const float mu = wave_sum((s4[0] + s4[1]) + (s4[2] + s4[3])) * (1.f / CW);
;         a0 -= mu; a1 -= mu;
;         const f32x4 q4 = a0 * a0 + a1 * a1;
;         const float r = __builtin_amdgcn_rsqf(wave_sum((q4[0] + q4[1]) + (q4[2] + q4[3])) * (1.f / CW) + EPS);
;         const f32x4 rg0 = g0 * r, rg1 = g1 * r;
;         const f32x4 z0 = a0 * rg0 + c0, z1 = a1 * rg1 + c1;
;         const f32x4 t0 = z0 * NLOG2E, t1 = z1 * NLOG2E;
;         const f32x4 d0 = (f32x4){__builtin_amdgcn_exp2f(t0[0]), __builtin_amdgcn_exp2f(t0[1]), __builtin_amdgcn_exp2f(t0[2]), __builtin_amdgcn_exp2f(t0[3])} + 1.f;
;         const f32x4 d1 = (f32x4){__builtin_amdgcn_exp2f(t1[0]), __builtin_amdgcn_exp2f(t1[1]), __builtin_amdgcn_exp2f(t1[2]), __builtin_amdgcn_exp2f(t1[3])} + 1.f;
;         const f32x4 y0 = z0 * (f32x4){__builtin_amdgcn_rcpf(d0[0]), __builtin_amdgcn_rcpf(d0[1]), __builtin_amdgcn_rcpf(d0[2]), __builtin_amdgcn_rcpf(d0[3])};
;         const f32x4 y1 = z1 * (f32x4){__builtin_amdgcn_rcpf(d1[0]), __builtin_amdgcn_rcpf(d1[1]), __builtin_amdgcn_rcpf(d1[2]), __builtin_amdgcn_rcpf(d1[3])};
;         v4u o; o.x = pk2(y0[0], y0[1]); o.y = pk2(y0[2], y0[3]); o.z = pk2(y1[0], y1[1]); o.w = pk2(y1[2], y1[3]);
;         *(GAS v4u*)(MIX + (size_t)(r0 + wave * CONV_RW + j) * DM + AW + 8 * lane) = o;
	v_pk_fma_f16 v21, v36, v32, v18
	v_pk_fma_f16 v20, v37, v33, v24
	v_cvt_f32_f16_e32 v18, v45
	v_cvt_f32_f16_sdwa v19, v45 dst_sel:DWORD dst_unused:UNUSED_PAD src0_sel:WORD_1
	v_cvt_f32_f16_e32 v24, v46
	v_cvt_f32_f16_sdwa v25, v46 dst_sel:DWORD dst_unused:UNUSED_PAD src0_sel:WORD_1
	v_cvt_f32_f16_e32 v28, v47
	v_cvt_f32_f16_e32 v30, v48
	v_cvt_f32_f16_sdwa v31, v48 dst_sel:DWORD dst_unused:UNUSED_PAD src0_sel:WORD_1
	v_cvt_f32_f16_sdwa v29, v47 dst_sel:DWORD dst_unused:UNUSED_PAD src0_sel:WORD_1
	v_pk_fma_f16 v51, v22, v38, v58
	v_pk_fma_f16 v22, v38, v34, v27
	v_pk_add_f32 v[24:25], v[24:25], v[30:31]
	v_pk_add_f32 v[18:19], v[18:19], v[28:29]
	v_pk_fma_f16 v40, v40, v36, v52
	v_add_f32_e32 v18, v18, v19
	v_add_f32_e32 v19, v24, v25
	v_add_f32_e32 v18, v18, v19
	v_pk_fma_f16 v52, v23, v39, v59
	v_pk_fma_f16 v23, v39, v35, v44
	v_add_f32_dpp v18, v18, v18 quad_perm:[1,0,3,2] row_mask:0xf bank_mask:0xf bound_ctrl:1
	v_pk_fma_f16 v41, v41, v37, v53
	v_pk_fma_f16 v42, v42, v38, v54
	v_add_f32_dpp v18, v18, v18 quad_perm:[2,3,0,1] row_mask:0xf bank_mask:0xf bound_ctrl:1
	v_pk_fma_f16 v43, v43, v39, v55
	s_mov_b32 s4, 0xbfb8aa3b
	v_add_f32_dpp v18, v18, v18 row_half_mirror row_mask:0xf bank_mask:0xf bound_ctrl:1
	s_add_i32 s0, s10, s53
	s_ashr_i32 s1, s0, 31
	v_add_f32_dpp v18, v18, v18 row_mirror row_mask:0xf bank_mask:0xf bound_ctrl:1
	v_mov_b32_e32 v19, v18
	s_nop 1
	v_permlane32_swap_b32_e32 v18, v19
	v_add_f32_e32 v18, v18, v19
	v_mov_b32_e32 v19, v18
	s_nop 1
	v_permlane16_swap_b32_e32 v18, v19
	v_add_f32_e32 v27, v18, v19
	v_fma_mix_f32 v29, v27, s57, v48 op_sel:[0,0,1] op_sel_hi:[0,0,1]
	v_fma_mix_f32 v28, v27, s57, v48 op_sel_hi:[0,0,1]
	v_fma_mix_f32 v31, v27, s57, v47 op_sel:[0,0,1] op_sel_hi:[0,0,1]
	v_fma_mix_f32 v30, v27, s57, v47 op_sel_hi:[0,0,1]
	v_fma_mix_f32 v19, v27, s57, v45 op_sel:[0,0,1] op_sel_hi:[0,0,1]
	v_fma_mix_f32 v18, v27, s57, v45 op_sel_hi:[0,0,1]
	v_fma_mix_f32 v25, v27, s57, v46 op_sel:[0,0,1] op_sel_hi:[0,0,1]
	v_fma_mix_f32 v24, v27, s57, v46 op_sel_hi:[0,0,1]
	v_pk_mul_f32 v[32:33], v[30:31], v[30:31]
	v_pk_mul_f32 v[34:35], v[28:29], v[28:29]
	v_pk_fma_f32 v[32:33], v[18:19], v[18:19], v[32:33]
	v_pk_fma_f32 v[34:35], v[24:25], v[24:25], v[34:35]
	v_add_f32_e32 v27, v32, v33
	v_add_f32_e32 v32, v34, v35
	v_add_f32_e32 v27, v27, v32
	s_lshl_b64 s[10:11], s[0:1], 11
	s_add_u32 s10, s70, s10
	v_add_f32_dpp v27, v27, v27 quad_perm:[1,0,3,2] row_mask:0xf bank_mask:0xf bound_ctrl:1
	s_addc_u32 s11, s71, s11
	s_nop 0
	v_add_f32_dpp v27, v27, v27 quad_perm:[2,3,0,1] row_mask:0xf bank_mask:0xf bound_ctrl:1
	s_nop 1
	v_add_f32_dpp v27, v27, v27 row_half_mirror row_mask:0xf bank_mask:0xf bound_ctrl:1
	s_nop 1
	v_add_f32_dpp v27, v27, v27 row_mirror row_mask:0xf bank_mask:0xf bound_ctrl:1
	v_mov_b32_e32 v32, v27
	s_nop 1
	v_permlane32_swap_b32_e32 v27, v32
	v_add_f32_e32 v27, v27, v32
	v_mov_b32_e32 v32, v27
	s_nop 1
	v_permlane16_swap_b32_e32 v27, v32
	v_add_f32_e32 v27, v27, v32
	v_fmamk_f32 v27, v27, 0x3b000000, v216
	v_rsq_f32_e32 v32, v27
	s_nop 0
	v_pk_mul_f32 v[34:35], v[16:17], v[32:33] op_sel_hi:[1,0]
	v_pk_mul_f32 v[36:37], v[14:15], v[32:33] op_sel_hi:[1,0]
	v_pk_mul_f32 v[38:39], v[4:5], v[32:33] op_sel_hi:[1,0]
	v_pk_mul_f32 v[32:33], v[2:3], v[32:33] op_sel_hi:[1,0]
	v_pk_fma_f32 v[18:19], v[18:19], v[36:37], v[10:11]
	v_pk_fma_f32 v[24:25], v[24:25], v[34:35], v[12:13]
	v_pk_fma_f32 v[30:31], v[30:31], v[32:33], v[6:7]
	v_pk_fma_f32 v[28:29], v[28:29], v[38:39], v[8:9]
	v_pk_mul_f32 v[32:33], s[4:5], v[24:25] op_sel_hi:[0,1]
	v_pk_mul_f32 v[34:35], s[4:5], v[18:19] op_sel_hi:[0,1]
	v_pk_mul_f32 v[36:37], s[4:5], v[28:29] op_sel_hi:[0,1]
	v_pk_mul_f32 v[38:39], s[4:5], v[30:31] op_sel_hi:[0,1]
	v_exp_f32_e32 v34, v34
	v_exp_f32_e32 v35, v35
	v_exp_f32_e32 v32, v32
	v_exp_f32_e32 v33, v33
	v_exp_f32_e32 v38, v38
	v_exp_f32_e32 v36, v36
	v_exp_f32_e32 v37, v37
	v_exp_f32_e32 v39, v39
	v_pk_add_f32 v[32:33], v[32:33], 1.0 op_sel_hi:[1,0]
	v_pk_add_f32 v[34:35], v[34:35], 1.0 op_sel_hi:[1,0]
	v_pk_add_f32 v[36:37], v[36:37], 1.0 op_sel_hi:[1,0]
	v_pk_add_f32 v[38:39], v[38:39], 1.0 op_sel_hi:[1,0]
	v_rcp_f32_e32 v34, v34
	v_rcp_f32_e32 v35, v35
	v_rcp_f32_e32 v32, v32
	v_rcp_f32_e32 v33, v33
	v_rcp_f32_e32 v38, v38
	v_rcp_f32_e32 v36, v36
	v_rcp_f32_e32 v37, v37
	v_rcp_f32_e32 v39, v39
	v_pk_mul_f32 v[24:25], v[24:25], v[32:33]
	v_pk_mul_f32 v[18:19], v[18:19], v[34:35]
	v_pk_mul_f32 v[32:33], v[28:29], v[36:37]
	v_pk_mul_f32 v[30:31], v[30:31], v[38:39]
	v_cvt_pk_bf16_f32 v28, v18, v19
	v_cvt_pk_bf16_f32 v29, v24, v25
	v_cvt_f32_f16_e32 v18, v40
	v_cvt_pk_bf16_f32 v30, v30, v31
	v_cvt_pk_bf16_f32 v31, v32, v33
	v_cvt_f32_f16_sdwa v19, v40 dst_sel:DWORD dst_unused:UNUSED_PAD src0_sel:WORD_1
	v_cvt_f32_f16_e32 v24, v41
	v_cvt_f32_f16_sdwa v25, v41 dst_sel:DWORD dst_unused:UNUSED_PAD src0_sel:WORD_1
	v_cvt_f32_f16_e32 v32, v42
	v_cvt_f32_f16_e32 v34, v43
	v_cvt_f32_f16_sdwa v35, v43 dst_sel:DWORD dst_unused:UNUSED_PAD src0_sel:WORD_1
	v_cvt_f32_f16_sdwa v33, v42 dst_sel:DWORD dst_unused:UNUSED_PAD src0_sel:WORD_1
	v_pk_add_f32 v[24:25], v[24:25], v[34:35]
	v_pk_add_f32 v[18:19], v[18:19], v[32:33]
	s_nop 0
	v_add_f32_e32 v18, v18, v19
	v_add_f32_e32 v19, v24, v25
	v_add_f32_e32 v18, v18, v19
	s_nop 1
	v_add_f32_dpp v18, v18, v18 quad_perm:[1,0,3,2] row_mask:0xf bank_mask:0xf bound_ctrl:1
	s_nop 1
	v_add_f32_dpp v18, v18, v18 quad_perm:[2,3,0,1] row_mask:0xf bank_mask:0xf bound_ctrl:1
	s_nop 1
	v_add_f32_dpp v18, v18, v18 row_half_mirror row_mask:0xf bank_mask:0xf bound_ctrl:1
	s_nop 1
	v_add_f32_dpp v18, v18, v18 row_mirror row_mask:0xf bank_mask:0xf bound_ctrl:1
	v_mov_b32_e32 v19, v18
	s_nop 1
; #define GAS __attribute__((address_space(1)))
; __device__ __forceinline__ unsigned pk2(float lo, float hi) { return pg8::cvt_pk_bf16(lo, hi); }
; __device__ __forceinline__ void conv_unit(int cu, const bf16* U, const unsigned char* cw16, const float* cb, const float* lg, const float* lb, bf16* MIX, LAS unsigned char* lds, int tid, int wave, int lane, bool& w_staged, unsigned& nx, gu32* qctr) {
;     ...
; #pragma unroll
;     for (int j = 0; j < CONV_RW; ++j) {
;         f32x4 a0 = {(float)hacc[j][0][0], (float)hacc[j][0][1], (float)hacc[j][1][0], (float)hacc[j][1][1]}, a1 = {(float)hacc[j][2][0], (float)hacc[j][2][1], (float)hacc[j][3][0], (float)hacc[j][3][1]};
;         const f32x4 s4 = a0 + a1;
;         const float mu = wave_sum((s4[0] + s4[1]) + (s4[2] + s4[3])) * (1.f / CW);
;         a0 -= mu; a1 -= mu;
;         const f32x4 q4 = a0 * a0 + a1 * a1;
;         const float r = __builtin_amdgcn_rsqf(wave_sum((q4[0] + q4[1]) + (q4[2] + q4[3])) * (1.f / CW) + EPS);
;         const f32x4 rg0 = g0 * r, rg1 = g1 * r;
;         const f32x4 z0 = a0 * rg0 + c0, z1 = a1 * rg1 + c1;
;         const f32x4 t0 = z0 * NLOG2E, t1 = z1 * NLOG2E;
;         const f32x4 d0 = (f32x4){__builtin_amdgcn_exp2f(t0[0]), __builtin_amdgcn_exp2f(t0[1]), __builtin_amdgcn_exp2f(t0[2]), __builtin_amdgcn_exp2f(t0[3])} + 1.f;
;         const f32x4 d1 = (f32x4){__builtin_amdgcn_exp2f(t1[0]), __builtin_amdgcn_exp2f(t1[1]), __builtin_amdgcn_exp2f(t1[2]), __builtin_amdgcn_exp2f(t1[3])} + 1.f;
;         const f32x4 y0 = z0 * (f32x4){__builtin_amdgcn_rcpf(d0[0]), __builtin_amdgcn_rcpf(d0[1]), __builtin_amdgcn_rcpf(d0[2]), __builtin_amdgcn_rcpf(d0[3])};
;         const f32x4 y1 = z1 * (f32x4){__builtin_amdgcn_rcpf(d1[0]), __builtin_amdgcn_rcpf(d1[1]), __builtin_amdgcn_rcpf(d1[2]), __builtin_amdgcn_rcpf(d1[3])};
;         v4u o; o.x = pk2(y0[0], y0[1]); o.y = pk2(y0[2], y0[3]); o.z = pk2(y1[0], y1[1]); o.w = pk2(y1[2], y1[3]);
;         *(GAS v4u*)(MIX + (size_t)(r0 + wave * CONV_RW + j) * DM + AW + 8 * lane) = o;
	v_permlane32_swap_b32_e32 v18, v19
	v_add_f32_e32 v18, v18, v19
	v_mov_b32_e32 v19, v18
	s_nop 1
	v_permlane16_swap_b32_e32 v18, v19
	v_add_f32_e32 v18, v18, v19
	v_fma_mix_f32 v35, v18, s57, v43 op_sel:[0,0,1] op_sel_hi:[0,0,1]
	v_fma_mix_f32 v34, v18, s57, v43 op_sel_hi:[0,0,1]
	v_fma_mix_f32 v37, v18, s57, v42 op_sel:[0,0,1] op_sel_hi:[0,0,1]
	v_fma_mix_f32 v36, v18, s57, v42 op_sel_hi:[0,0,1]
	v_fma_mix_f32 v25, v18, s57, v40 op_sel:[0,0,1] op_sel_hi:[0,0,1]
	v_fma_mix_f32 v24, v18, s57, v40 op_sel_hi:[0,0,1]
	v_fma_mix_f32 v33, v18, s57, v41 op_sel:[0,0,1] op_sel_hi:[0,0,1]
	v_fma_mix_f32 v32, v18, s57, v41 op_sel_hi:[0,0,1]
	v_pk_mul_f32 v[18:19], v[36:37], v[36:37]
	v_pk_mul_f32 v[38:39], v[34:35], v[34:35]
	v_pk_fma_f32 v[18:19], v[24:25], v[24:25], v[18:19]
	v_pk_fma_f32 v[38:39], v[32:33], v[32:33], v[38:39]
	v_add_f32_e32 v18, v18, v19
	v_add_f32_e32 v19, v38, v39
	v_add_f32_e32 v18, v18, v19
	s_nop 1
	v_add_f32_dpp v18, v18, v18 quad_perm:[1,0,3,2] row_mask:0xf bank_mask:0xf bound_ctrl:1
	s_nop 1
	v_add_f32_dpp v18, v18, v18 quad_perm:[2,3,0,1] row_mask:0xf bank_mask:0xf bound_ctrl:1
	s_nop 1
	v_add_f32_dpp v18, v18, v18 row_half_mirror row_mask:0xf bank_mask:0xf bound_ctrl:1
	s_nop 1
	v_add_f32_dpp v18, v18, v18 row_mirror row_mask:0xf bank_mask:0xf bound_ctrl:1
	v_mov_b32_e32 v19, v18
	s_nop 1
	v_permlane32_swap_b32_e32 v18, v19
	v_add_f32_e32 v18, v18, v19
	v_mov_b32_e32 v19, v18
	s_nop 1
	v_permlane16_swap_b32_e32 v18, v19
	v_add_f32_e32 v18, v18, v19
	v_fmamk_f32 v18, v18, 0x3b000000, v216
	v_rsq_f32_e32 v38, v18
	v_lshlrev_b64 v[18:19], 1, v[74:75]
	v_lshl_add_u64 v[40:41], s[10:11], 0, v[18:19]
	global_store_dwordx4 v[40:41], v[28:31], off offset:1024
	v_pk_mul_f32 v[40:41], v[4:5], v[38:39] op_sel_hi:[1,0]
	s_or_b32 s10, s0, 1
	v_pk_mul_f32 v[28:29], v[16:17], v[38:39] op_sel_hi:[1,0]
	v_pk_mul_f32 v[30:31], v[14:15], v[38:39] op_sel_hi:[1,0]
	v_pk_mul_f32 v[38:39], v[2:3], v[38:39] op_sel_hi:[1,0]
	v_pk_fma_f32 v[24:25], v[24:25], v[30:31], v[10:11]
	v_pk_fma_f32 v[28:29], v[32:33], v[28:29], v[12:13]
	v_pk_fma_f32 v[30:31], v[36:37], v[38:39], v[6:7]
	v_pk_fma_f32 v[32:33], v[34:35], v[40:41], v[8:9]
	v_pk_mul_f32 v[34:35], s[4:5], v[28:29] op_sel_hi:[0,1]
	v_pk_mul_f32 v[36:37], s[4:5], v[24:25] op_sel_hi:[0,1]
	v_pk_mul_f32 v[38:39], s[4:5], v[32:33] op_sel_hi:[0,1]
	v_pk_mul_f32 v[40:41], s[4:5], v[30:31] op_sel_hi:[0,1]
	v_exp_f32_e32 v36, v36
	v_exp_f32_e32 v37, v37
	v_exp_f32_e32 v34, v34
	v_exp_f32_e32 v35, v35
	v_exp_f32_e32 v40, v40
	v_exp_f32_e32 v38, v38
	v_exp_f32_e32 v39, v39
	v_exp_f32_e32 v41, v41
	v_pk_add_f32 v[34:35], v[34:35], 1.0 op_sel_hi:[1,0]
	v_pk_add_f32 v[36:37], v[36:37], 1.0 op_sel_hi:[1,0]
	v_pk_add_f32 v[38:39], v[38:39], 1.0 op_sel_hi:[1,0]
	v_pk_add_f32 v[40:41], v[40:41], 1.0 op_sel_hi:[1,0]
	v_rcp_f32_e32 v36, v36
	v_rcp_f32_e32 v37, v37
	v_rcp_f32_e32 v34, v34
	v_rcp_f32_e32 v35, v35
	v_rcp_f32_e32 v40, v40
	v_rcp_f32_e32 v38, v38
	v_rcp_f32_e32 v39, v39
	v_rcp_f32_e32 v41, v41
	v_pk_mul_f32 v[34:35], v[28:29], v[34:35]
	v_pk_mul_f32 v[24:25], v[24:25], v[36:37]
	v_pk_mul_f32 v[32:33], v[32:33], v[38:39]
	v_pk_mul_f32 v[30:31], v[30:31], v[40:41]
	v_cvt_pk_bf16_f32 v28, v24, v25
	v_cvt_pk_bf16_f32 v29, v34, v35
	v_cvt_f32_f16_e32 v24, v49
	v_cvt_pk_bf16_f32 v30, v30, v31
	v_cvt_pk_bf16_f32 v31, v32, v33
	v_cvt_f32_f16_sdwa v25, v49 dst_sel:DWORD dst_unused:UNUSED_PAD src0_sel:WORD_1
	v_cvt_f32_f16_e32 v32, v50
	v_cvt_f32_f16_sdwa v33, v50 dst_sel:DWORD dst_unused:UNUSED_PAD src0_sel:WORD_1
	v_cvt_f32_f16_e32 v34, v51
	v_cvt_f32_f16_e32 v36, v52
	v_cvt_f32_f16_sdwa v37, v52 dst_sel:DWORD dst_unused:UNUSED_PAD src0_sel:WORD_1
	v_cvt_f32_f16_sdwa v35, v51 dst_sel:DWORD dst_unused:UNUSED_PAD src0_sel:WORD_1
	s_ashr_i32 s11, s10, 31
	s_lshl_b64 s[10:11], s[10:11], 11
	v_pk_add_f32 v[32:33], v[32:33], v[36:37]
	v_pk_add_f32 v[24:25], v[24:25], v[34:35]
	s_add_u32 s10, s70, s10
	v_add_f32_e32 v24, v24, v25
	v_add_f32_e32 v25, v32, v33
	v_add_f32_e32 v24, v24, v25
	s_addc_u32 s11, s71, s11
	s_nop 0
	v_add_f32_dpp v24, v24, v24 quad_perm:[1,0,3,2] row_mask:0xf bank_mask:0xf bound_ctrl:1
	s_nop 1
	v_add_f32_dpp v24, v24, v24 quad_perm:[2,3,0,1] row_mask:0xf bank_mask:0xf bound_ctrl:1
	s_nop 1
	v_add_f32_dpp v24, v24, v24 row_half_mirror row_mask:0xf bank_mask:0xf bound_ctrl:1
	s_nop 1
	v_add_f32_dpp v24, v24, v24 row_mirror row_mask:0xf bank_mask:0xf bound_ctrl:1
	v_mov_b32_e32 v25, v24
	s_nop 1
	v_permlane32_swap_b32_e32 v24, v25
	v_add_f32_e32 v24, v24, v25
	v_mov_b32_e32 v25, v24
	s_nop 1
	v_permlane16_swap_b32_e32 v24, v25
	v_add_f32_e32 v27, v24, v25
	v_fma_mix_f32 v35, v27, s57, v52 op_sel:[0,0,1] op_sel_hi:[0,0,1]
	v_fma_mix_f32 v34, v27, s57, v52 op_sel_hi:[0,0,1]
	v_fma_mix_f32 v37, v27, s57, v51 op_sel:[0,0,1] op_sel_hi:[0,0,1]
	v_fma_mix_f32 v36, v27, s57, v51 op_sel_hi:[0,0,1]
	v_fma_mix_f32 v25, v27, s57, v49 op_sel:[0,0,1] op_sel_hi:[0,0,1]
	v_fma_mix_f32 v24, v27, s57, v49 op_sel_hi:[0,0,1]
	v_fma_mix_f32 v33, v27, s57, v50 op_sel:[0,0,1] op_sel_hi:[0,0,1]
	v_fma_mix_f32 v32, v27, s57, v50 op_sel_hi:[0,0,1]
	v_pk_mul_f32 v[38:39], v[36:37], v[36:37]
	v_pk_mul_f32 v[40:41], v[34:35], v[34:35]
	v_pk_fma_f32 v[38:39], v[24:25], v[24:25], v[38:39]
	v_pk_fma_f32 v[40:41], v[32:33], v[32:33], v[40:41]
	v_add_f32_e32 v27, v38, v39
	v_add_f32_e32 v38, v40, v41
	v_add_f32_e32 v27, v27, v38
	v_lshl_add_u64 v[40:41], s[10:11], 0, v[18:19]
	global_store_dwordx4 v[40:41], v[28:31], off offset:1024
	v_add_f32_dpp v27, v27, v27 quad_perm:[1,0,3,2] row_mask:0xf bank_mask:0xf bound_ctrl:1
	s_or_b32 s10, s0, 2
	s_ashr_i32 s11, s10, 31
	v_add_f32_dpp v27, v27, v27 quad_perm:[2,3,0,1] row_mask:0xf bank_mask:0xf bound_ctrl:1
; #define GAS __attribute__((address_space(1)))
; __device__ __forceinline__ unsigned pk2(float lo, float hi) { return pg8::cvt_pk_bf16(lo, hi); }
; __device__ __forceinline__ void conv_unit(int cu, const bf16* U, const unsigned char* cw16, const float* cb, const float* lg, const float* lb, bf16* MIX, LAS unsigned char* lds, int tid, int wave, int lane, bool& w_staged, unsigned& nx, gu32* qctr) {
;     ...
; #pragma unroll
;     for (int j = 0; j < CONV_RW; ++j) {
;         f32x4 a0 = {(float)hacc[j][0][0], (float)hacc[j][0][1], (float)hacc[j][1][0], (float)hacc[j][1][1]}, a1 = {(float)hacc[j][2][0], (float)hacc[j][2][1], (float)hacc[j][3][0], (float)hacc[j][3][1]};
;         const f32x4 s4 = a0 + a1;
;         const float mu = wave_sum((s4[0] + s4[1]) + (s4[2] + s4[3])) * (1.f / CW);
;         a0 -= mu; a1 -= mu;
;         const f32x4 q4 = a0 * a0 + a1 * a1;
;         const float r = __builtin_amdgcn_rsqf(wave_sum((q4[0] + q4[1]) + (q4[2] + q4[3])) * (1.f / CW) + EPS);
;         const f32x4 rg0 = g0 * r, rg1 = g1 * r;
;         const f32x4 z0 = a0 * rg0 + c0, z1 = a1 * rg1 + c1;
;         const f32x4 t0 = z0 * NLOG2E, t1 = z1 * NLOG2E;
;         const f32x4 d0 = (f32x4){__builtin_amdgcn_exp2f(t0[0]), __builtin_amdgcn_exp2f(t0[1]), __builtin_amdgcn_exp2f(t0[2]), __builtin_amdgcn_exp2f(t0[3])} + 1.f;
;         const f32x4 d1 = (f32x4){__builtin_amdgcn_exp2f(t1[0]), __builtin_amdgcn_exp2f(t1[1]), __builtin_amdgcn_exp2f(t1[2]), __builtin_amdgcn_exp2f(t1[3])} + 1.f;
;         const f32x4 y0 = z0 * (f32x4){__builtin_amdgcn_rcpf(d0[0]), __builtin_amdgcn_rcpf(d0[1]), __builtin_amdgcn_rcpf(d0[2]), __builtin_amdgcn_rcpf(d0[3])};
;         const f32x4 y1 = z1 * (f32x4){__builtin_amdgcn_rcpf(d1[0]), __builtin_amdgcn_rcpf(d1[1]), __builtin_amdgcn_rcpf(d1[2]), __builtin_amdgcn_rcpf(d1[3])};
;         v4u o; o.x = pk2(y0[0], y0[1]); o.y = pk2(y0[2], y0[3]); o.z = pk2(y1[0], y1[1]); o.w = pk2(y1[2], y1[3]);
;         *(GAS v4u*)(MIX + (size_t)(r0 + wave * CONV_RW + j) * DM + AW + 8 * lane) = o;
;     }
;     asm volatile("s_waitcnt lgkmcnt(0)\n\ts_barrier" ::: "memory");
	s_lshl_b64 s[10:11], s[10:11], 11
	s_add_u32 s10, s70, s10
	v_add_f32_dpp v27, v27, v27 row_half_mirror row_mask:0xf bank_mask:0xf bound_ctrl:1
	s_addc_u32 s11, s71, s11
	s_or_b32 s0, s0, 3
	v_add_f32_dpp v27, v27, v27 row_mirror row_mask:0xf bank_mask:0xf bound_ctrl:1
	v_mov_b32_e32 v38, v27
	s_nop 1
	v_permlane32_swap_b32_e32 v27, v38
	v_add_f32_e32 v27, v27, v38
	v_mov_b32_e32 v38, v27
	s_nop 1
	v_permlane16_swap_b32_e32 v27, v38
	v_add_f32_e32 v27, v27, v38
	v_fmamk_f32 v27, v27, 0x3b000000, v216
	v_rsq_f32_e32 v38, v27
	s_ashr_i32 s1, s0, 31
	s_lshl_b64 s[0:1], s[0:1], 11
	s_add_u32 s0, s70, s0
	v_pk_mul_f32 v[28:29], v[16:17], v[38:39] op_sel_hi:[1,0]
	v_pk_mul_f32 v[30:31], v[14:15], v[38:39] op_sel_hi:[1,0]
	v_pk_mul_f32 v[40:41], v[4:5], v[38:39] op_sel_hi:[1,0]
	v_pk_mul_f32 v[38:39], v[2:3], v[38:39] op_sel_hi:[1,0]
	v_pk_fma_f32 v[24:25], v[24:25], v[30:31], v[10:11]
	v_pk_fma_f32 v[28:29], v[32:33], v[28:29], v[12:13]
	v_pk_fma_f32 v[30:31], v[36:37], v[38:39], v[6:7]
	v_pk_fma_f32 v[32:33], v[34:35], v[40:41], v[8:9]
	v_pk_mul_f32 v[34:35], s[4:5], v[28:29] op_sel_hi:[0,1]
	v_pk_mul_f32 v[36:37], s[4:5], v[24:25] op_sel_hi:[0,1]
	v_pk_mul_f32 v[38:39], s[4:5], v[32:33] op_sel_hi:[0,1]
	v_pk_mul_f32 v[40:41], s[4:5], v[30:31] op_sel_hi:[0,1]
	v_exp_f32_e32 v36, v36
	v_exp_f32_e32 v37, v37
	v_exp_f32_e32 v34, v34
	v_exp_f32_e32 v35, v35
	v_exp_f32_e32 v40, v40
	v_exp_f32_e32 v38, v38
	v_exp_f32_e32 v39, v39
	v_exp_f32_e32 v41, v41
	v_pk_add_f32 v[34:35], v[34:35], 1.0 op_sel_hi:[1,0]
	v_pk_add_f32 v[36:37], v[36:37], 1.0 op_sel_hi:[1,0]
	v_pk_add_f32 v[38:39], v[38:39], 1.0 op_sel_hi:[1,0]
	v_pk_add_f32 v[40:41], v[40:41], 1.0 op_sel_hi:[1,0]
	v_rcp_f32_e32 v36, v36
	v_rcp_f32_e32 v37, v37
	v_rcp_f32_e32 v34, v34
	v_rcp_f32_e32 v35, v35
	v_rcp_f32_e32 v40, v40
	v_rcp_f32_e32 v38, v38
	v_rcp_f32_e32 v39, v39
	v_rcp_f32_e32 v41, v41
	v_pk_mul_f32 v[34:35], v[28:29], v[34:35]
	v_pk_mul_f32 v[24:25], v[24:25], v[36:37]
	v_pk_mul_f32 v[32:33], v[32:33], v[38:39]
	v_pk_mul_f32 v[30:31], v[30:31], v[40:41]
	v_cvt_pk_bf16_f32 v28, v24, v25
	v_cvt_pk_bf16_f32 v29, v34, v35
	v_cvt_f32_f16_e32 v24, v21
	v_cvt_pk_bf16_f32 v30, v30, v31
	v_cvt_pk_bf16_f32 v31, v32, v33
	v_cvt_f32_f16_sdwa v25, v21 dst_sel:DWORD dst_unused:UNUSED_PAD src0_sel:WORD_1
	v_cvt_f32_f16_e32 v32, v20
	v_cvt_f32_f16_sdwa v33, v20 dst_sel:DWORD dst_unused:UNUSED_PAD src0_sel:WORD_1
	v_cvt_f32_f16_e32 v34, v22
	v_cvt_f32_f16_e32 v36, v23
	v_cvt_f32_f16_sdwa v37, v23 dst_sel:DWORD dst_unused:UNUSED_PAD src0_sel:WORD_1
	v_cvt_f32_f16_sdwa v35, v22 dst_sel:DWORD dst_unused:UNUSED_PAD src0_sel:WORD_1
	s_addc_u32 s1, s71, s1
	v_pk_add_f32 v[32:33], v[32:33], v[36:37]
	v_pk_add_f32 v[24:25], v[24:25], v[34:35]
	s_nop 0
	v_add_f32_e32 v24, v24, v25
	v_add_f32_e32 v25, v32, v33
	v_add_f32_e32 v24, v24, v25
	s_nop 1
	v_add_f32_dpp v24, v24, v24 quad_perm:[1,0,3,2] row_mask:0xf bank_mask:0xf bound_ctrl:1
	s_nop 1
	v_add_f32_dpp v24, v24, v24 quad_perm:[2,3,0,1] row_mask:0xf bank_mask:0xf bound_ctrl:1
	s_nop 1
	v_add_f32_dpp v24, v24, v24 row_half_mirror row_mask:0xf bank_mask:0xf bound_ctrl:1
	s_nop 1
	v_add_f32_dpp v24, v24, v24 row_mirror row_mask:0xf bank_mask:0xf bound_ctrl:1
	v_mov_b32_e32 v25, v24
	s_nop 1
	v_permlane32_swap_b32_e32 v24, v25
	v_add_f32_e32 v24, v24, v25
	v_mov_b32_e32 v25, v24
	s_nop 1
	v_permlane16_swap_b32_e32 v24, v25
	v_add_f32_e32 v27, v24, v25
	v_fma_mix_f32 v33, v27, s57, v23 op_sel:[0,0,1] op_sel_hi:[0,0,1]
	v_fma_mix_f32 v32, v27, s57, v23 op_sel_hi:[0,0,1]
	v_fma_mix_f32 v23, v27, s57, v22 op_sel:[0,0,1] op_sel_hi:[0,0,1]
	v_fma_mix_f32 v22, v27, s57, v22 op_sel_hi:[0,0,1]
	v_fma_mix_f32 v25, v27, s57, v21 op_sel:[0,0,1] op_sel_hi:[0,0,1]
	v_fma_mix_f32 v24, v27, s57, v21 op_sel_hi:[0,0,1]
	v_fma_mix_f32 v21, v27, s57, v20 op_sel:[0,0,1] op_sel_hi:[0,0,1]
	v_fma_mix_f32 v20, v27, s57, v20 op_sel_hi:[0,0,1]
	v_pk_mul_f32 v[34:35], v[22:23], v[22:23]
	v_pk_mul_f32 v[36:37], v[32:33], v[32:33]
	v_pk_fma_f32 v[34:35], v[24:25], v[24:25], v[34:35]
	v_pk_fma_f32 v[36:37], v[20:21], v[20:21], v[36:37]
	v_add_f32_e32 v27, v34, v35
	v_add_f32_e32 v34, v36, v37
	v_add_f32_e32 v27, v27, v34
	v_lshl_add_u64 v[36:37], s[10:11], 0, v[18:19]
	global_store_dwordx4 v[36:37], v[28:31], off offset:1024
	v_add_f32_dpp v27, v27, v27 quad_perm:[1,0,3,2] row_mask:0xf bank_mask:0xf bound_ctrl:1
	s_nop 1
	v_add_f32_dpp v27, v27, v27 quad_perm:[2,3,0,1] row_mask:0xf bank_mask:0xf bound_ctrl:1
	s_nop 1
	v_add_f32_dpp v27, v27, v27 row_half_mirror row_mask:0xf bank_mask:0xf bound_ctrl:1
	s_nop 1
	v_add_f32_dpp v27, v27, v27 row_mirror row_mask:0xf bank_mask:0xf bound_ctrl:1
	v_mov_b32_e32 v34, v27
	s_nop 1
	v_permlane32_swap_b32_e32 v27, v34
	v_add_f32_e32 v27, v27, v34
	v_mov_b32_e32 v34, v27
	s_nop 1
	v_permlane16_swap_b32_e32 v27, v34
	v_add_f32_e32 v27, v27, v34
	v_fmamk_f32 v27, v27, 0x3b000000, v216
	v_rsq_f32_e32 v34, v27
	s_nop 0
	v_pk_mul_f32 v[16:17], v[16:17], v[34:35] op_sel_hi:[1,0]
	v_pk_mul_f32 v[14:15], v[14:15], v[34:35] op_sel_hi:[1,0]
	v_pk_mul_f32 v[4:5], v[4:5], v[34:35] op_sel_hi:[1,0]
	v_pk_mul_f32 v[2:3], v[2:3], v[34:35] op_sel_hi:[1,0]
	v_pk_fma_f32 v[12:13], v[20:21], v[16:17], v[12:13]
	v_pk_fma_f32 v[10:11], v[24:25], v[14:15], v[10:11]
	v_pk_fma_f32 v[2:3], v[22:23], v[2:3], v[6:7]
	v_pk_fma_f32 v[4:5], v[32:33], v[4:5], v[8:9]
	v_pk_mul_f32 v[6:7], s[4:5], v[12:13] op_sel_hi:[0,1]
	v_pk_mul_f32 v[8:9], s[4:5], v[10:11] op_sel_hi:[0,1]
	v_pk_mul_f32 v[14:15], s[4:5], v[4:5] op_sel_hi:[0,1]
	v_pk_mul_f32 v[16:17], s[4:5], v[2:3] op_sel_hi:[0,1]
	v_exp_f32_e32 v6, v6
	v_exp_f32_e32 v7, v7
	v_exp_f32_e32 v8, v8
	v_exp_f32_e32 v9, v9
	v_exp_f32_e32 v16, v16
	v_exp_f32_e32 v14, v14
	v_exp_f32_e32 v15, v15
	v_exp_f32_e32 v17, v17
	v_pk_add_f32 v[6:7], v[6:7], 1.0 op_sel_hi:[1,0]
	v_pk_add_f32 v[8:9], v[8:9], 1.0 op_sel_hi:[1,0]
	v_pk_add_f32 v[14:15], v[14:15], 1.0 op_sel_hi:[1,0]
	v_pk_add_f32 v[16:17], v[16:17], 1.0 op_sel_hi:[1,0]
	v_rcp_f32_e32 v6, v6
	v_rcp_f32_e32 v7, v7
	v_rcp_f32_e32 v8, v8
	v_rcp_f32_e32 v9, v9
	v_rcp_f32_e32 v16, v16
	v_rcp_f32_e32 v14, v14
	v_rcp_f32_e32 v15, v15
	v_rcp_f32_e32 v17, v17
	v_pk_mul_f32 v[6:7], v[12:13], v[6:7]
	v_pk_mul_f32 v[8:9], v[10:11], v[8:9]
	v_pk_mul_f32 v[10:11], v[4:5], v[14:15]
	v_pk_mul_f32 v[4:5], v[2:3], v[16:17]
	v_cvt_pk_bf16_f32 v2, v8, v9
	v_cvt_pk_bf16_f32 v3, v6, v7
	v_lshl_add_u64 v[6:7], s[0:1], 0, v[18:19]
	v_cvt_pk_bf16_f32 v4, v4, v5
	v_cvt_pk_bf16_f32 v5, v10, v11
	global_store_dwordx4 v[6:7], v[2:5], off offset:1024
	s_waitcnt vmcnt(4)
; #define GAS __attribute__((address_space(1)))
; __device__ __forceinline__ unsigned pk2(float lo, float hi) { return pg8::cvt_pk_bf16(lo, hi); }
; __device__ __forceinline__ void conv_unit(int cu, const bf16* U, const unsigned char* cw16, const float* cb, const float* lg, const float* lb, bf16* MIX, LAS unsigned char* lds, int tid, int wave, int lane, bool& w_staged, unsigned& nx, gu32* qctr) {
;     ...
;         v4u o; o.x = pk2(y0[0], y0[1]); o.y = pk2(y0[2], y0[3]); o.z = pk2(y1[0], y1[1]); o.w = pk2(y1[2], y1[3]);
;         *(GAS v4u*)(MIX + (size_t)(r0 + wave * CONV_RW + j) * DM + AW + 8 * lane) = o;
;     }
;     asm volatile("s_waitcnt lgkmcnt(0)\n\ts_barrier" ::: "memory");
	v_cvt_pk_bf16_f32 v222, v130, v131
	v_cvt_pk_bf16_f32 v223, v132, v133
	global_store_dwordx2 v221, v[222:223], s[62:63]
	v_cvt_pk_bf16_f32 v222, v134, v135
	v_cvt_pk_bf16_f32 v223, v136, v137
	global_store_dwordx2 v221, v[222:223], s[62:63] offset:512
	v_cvt_pk_bf16_f32 v222, v138, v139
	v_cvt_pk_bf16_f32 v223, v140, v141
	global_store_dwordx2 v221, v[222:223], s[62:63] offset:1024
	v_cvt_pk_bf16_f32 v222, v142, v143
	v_cvt_pk_bf16_f32 v223, v144, v145
	global_store_dwordx2 v221, v[222:223], s[62:63] offset:1536
	s_waitcnt lgkmcnt(0)
	s_barrier
	s_mov_b64 s[0:1], 0
